# also peel first K-iteration of the 4 MoE-up loops (C=0 MFMAs, no accumulator zeroing)
# speedup vs baseline: 1.0133x; 1.0105x over previous
.LBB0_773:
	v_bfe_u32 v2, v193, 16, 16
	v_lshl_add_u32 v194, v2, 10, v1
	v_bfe_u32 v2, v192, 16, 16
	v_mov_b32_e32 v50, 0
	v_lshl_add_u32 v195, v2, 10, v1
	s_mov_b32 s8, -2
	s_movk_i32 s9, 0x100
	s_branch .LBB0_775_pr0

.LBB0_775:
	ds_read_b128 v[2:5], v190
	ds_read_b128 v[6:9], v190 offset:1024
	ds_read_b128 v[10:13], v190 offset:2048
	ds_read_b128 v[14:17], v190 offset:3072
	s_cmp_eq_u32 s8, 4
	s_cselect_b64 s[6:7], -1, 0
	s_add_i32 s14, s9, 0xffffff80
	s_cmp_lg_u32 s8, 4
	v_bfe_u32 v196, v186, 16, 16
	s_mov_b32 m0, s34
	v_lshl_add_u32 v196, v196, 10, v1
	v_bfe_u32 v197, v185, 16, 16
	ds_read_b128 v[42:45], v191
	ds_read_b128 v[46:49], v191 offset:1024
	ds_read_b128 v[34:37], v191 offset:2048
	ds_read_b128 v[38:41], v191 offset:3072
	ds_read_b128 v[26:29], v191 offset:4096
	ds_read_b128 v[30:33], v191 offset:5120
	ds_read_b128 v[18:21], v191 offset:6144
	ds_read_b128 v[22:25], v191 offset:7168
	buffer_load_dwordx4 v196, s[40:43], s14 offen lds
	v_lshl_add_u32 v197, v197, 10, v1
	s_mov_b32 m0, s35
	s_nop 0
	buffer_load_dwordx4 v197, s[40:43], s14 offen lds
	s_cbranch_scc1 .LBB0_774
	v_mov_b32_e32 v197, v195
	v_mov_b32_e32 v196, v194
	v_mov_b32_e32 v185, v192
	v_mov_b32_e32 v186, v193
	s_branch .LBB0_774
.LBB0_775_pr0:
	ds_read_b128 v[2:5], v190
	ds_read_b128 v[6:9], v190 offset:1024
	ds_read_b128 v[10:13], v190 offset:2048
	ds_read_b128 v[14:17], v190 offset:3072
	s_cmp_eq_u32 s8, 4
	s_cselect_b64 s[6:7], -1, 0
	s_add_i32 s14, s9, 0xffffff80
	s_cmp_lg_u32 s8, 4
	v_bfe_u32 v196, v186, 16, 16
	s_mov_b32 m0, s34
	v_lshl_add_u32 v196, v196, 10, v1
	v_bfe_u32 v197, v185, 16, 16
	ds_read_b128 v[42:45], v191
	ds_read_b128 v[46:49], v191 offset:1024
	ds_read_b128 v[34:37], v191 offset:2048
	ds_read_b128 v[38:41], v191 offset:3072
	ds_read_b128 v[26:29], v191 offset:4096
	ds_read_b128 v[30:33], v191 offset:5120
	ds_read_b128 v[18:21], v191 offset:6144
	ds_read_b128 v[22:25], v191 offset:7168
	buffer_load_dwordx4 v196, s[40:43], s14 offen lds
	v_lshl_add_u32 v197, v197, 10, v1
	s_mov_b32 m0, s35
	s_nop 0
	buffer_load_dwordx4 v197, s[40:43], s14 offen lds
	s_cbranch_scc1 .LBB0_774_pr0
	v_mov_b32_e32 v197, v195
	v_mov_b32_e32 v196, v194
	v_mov_b32_e32 v185, v192
	v_mov_b32_e32 v186, v193
	s_branch .LBB0_774_pr0
.LBB0_774_pr0:
	s_and_b64 s[14:15], s[6:7], exec
	s_cselect_b32 s57, 0, s9
	s_add_i32 s14, s50, s9
	s_or_b32 s51, s57, 0x80
	s_waitcnt lgkmcnt(8)
	s_barrier
	s_waitcnt lgkmcnt(0)
	s_and_b64 s[6:7], s[6:7], exec
	s_cselect_b32 s6, s46, s14
	s_add_i32 s7, s6, 0x80
	s_setprio 1
	s_waitcnt lgkmcnt(6)
	v_mfma_f32_16x16x128_f8f6f4 v[174:177], v[2:9], v[42:49], 0
	v_mfma_f32_16x16x128_f8f6f4 v[166:169], v[10:17], v[42:49], 0
	s_waitcnt lgkmcnt(4)
	v_mfma_f32_16x16x128_f8f6f4 v[158:161], v[2:9], v[34:41], 0
	v_mfma_f32_16x16x128_f8f6f4 v[150:153], v[10:17], v[34:41], 0
	s_waitcnt lgkmcnt(2)
	v_mfma_f32_16x16x128_f8f6f4 v[142:145], v[2:9], v[26:33], 0
	v_mfma_f32_16x16x128_f8f6f4 v[134:137], v[10:17], v[26:33], 0
	s_waitcnt lgkmcnt(0)
	v_mfma_f32_16x16x128_f8f6f4 v[126:129], v[2:9], v[18:25], 0
	v_mfma_f32_16x16x128_f8f6f4 v[118:121], v[10:17], v[18:25], 0
	s_setprio 0
	s_barrier
	s_mov_b32 m0, s18
	v_add_u32_e32 v210, 0x14000, v189
	s_mov_b32 s14, s42
	s_mov_b32 s15, s43
	ds_read_b128 v[198:201], v210
	ds_read_b128 v[202:205], v210 offset:1024
	ds_read_b128 v[206:209], v210 offset:2048
	ds_read_b128 v[210:213], v210 offset:3072
	buffer_load_dwordx4 v184, s[12:15], s6 offen lds
	s_add_i32 s33, s6, 0x10000
	s_mov_b32 m0, s19
	s_nop 0
	buffer_load_dwordx4 v184, s[12:15], s33 offen lds
	s_barrier
	s_waitcnt lgkmcnt(0)
	s_setprio 1
	s_waitcnt lgkmcnt(2)
	v_mfma_f32_16x16x128_f8f6f4 v[170:173], v[198:205], v[42:49], 0
	s_waitcnt lgkmcnt(0)
	v_mfma_f32_16x16x128_f8f6f4 v[162:165], v[206:213], v[42:49], 0
	v_mfma_f32_16x16x128_f8f6f4 v[154:157], v[198:205], v[34:41], 0
	v_mfma_f32_16x16x128_f8f6f4 v[146:149], v[206:213], v[34:41], 0
	v_mfma_f32_16x16x128_f8f6f4 v[138:141], v[198:205], v[26:33], 0
	v_mfma_f32_16x16x128_f8f6f4 v[130:133], v[206:213], v[26:33], 0
	v_mfma_f32_16x16x128_f8f6f4 v[122:125], v[198:205], v[18:25], 0
	v_mfma_f32_16x16x128_f8f6f4 v[114:117], v[206:213], v[18:25], 0
	s_setprio 0
	v_lshlrev_b32_e32 v214, 10, v186
	v_and_b32_e32 v214, 0x3fffc00, v214
	v_lshlrev_b32_e32 v215, 10, v185
	s_mov_b32 m0, s17
	v_add_u32_e32 v214, v214, v1
	v_and_b32_e32 v215, 0x3fffc00, v215
	s_barrier
	ds_read_b128 v[18:21], v191 offset:16384
	ds_read_b128 v[22:25], v191 offset:17408
	ds_read_b128 v[26:29], v191 offset:18432
	ds_read_b128 v[30:33], v191 offset:19456
	ds_read_b128 v[34:37], v191 offset:20480
	ds_read_b128 v[38:41], v191 offset:21504
	ds_read_b128 v[42:45], v191 offset:22528
	ds_read_b128 v[46:49], v191 offset:23552
	buffer_load_dwordx4 v214, s[40:43], s57 offen lds
	v_add_u32_e32 v215, v215, v1
	s_mov_b32 m0, s20
	s_nop 0
	buffer_load_dwordx4 v215, s[40:43], s57 offen lds
	s_barrier
	s_waitcnt lgkmcnt(0)
	s_setprio 1
	s_waitcnt lgkmcnt(6)
	v_mfma_f32_16x16x128_f8f6f4 v[110:113], v[2:9], v[18:25], 0
	v_mfma_f32_16x16x128_f8f6f4 v[102:105], v[10:17], v[18:25], 0
	s_waitcnt lgkmcnt(4)
	v_mfma_f32_16x16x128_f8f6f4 v[94:97], v[2:9], v[26:33], 0
	v_mfma_f32_16x16x128_f8f6f4 v[86:89], v[10:17], v[26:33], 0
	s_waitcnt lgkmcnt(2)
	v_mfma_f32_16x16x128_f8f6f4 v[78:81], v[2:9], v[34:41], 0
	v_mfma_f32_16x16x128_f8f6f4 v[70:73], v[10:17], v[34:41], 0
	s_waitcnt lgkmcnt(0)
	v_mfma_f32_16x16x128_f8f6f4 v[62:65], v[2:9], v[42:49], 0
	v_mfma_f32_16x16x128_f8f6f4 v[54:57], v[10:17], v[42:49], 0
	s_setprio 0
	s_barrier
	s_mov_b32 m0, s21
	s_add_i32 s33, s6, 0x20000
	buffer_load_dwordx4 v184, s[12:15], s33 offen lds
	s_add_i32 s33, s6, 0x30000
	s_mov_b32 m0, s22
	s_nop 0
	buffer_load_dwordx4 v184, s[12:15], s33 offen lds
	s_cmp_eq_u32 s100, 0
	s_cbranch_scc1 .Lfw_3_a_pr0
	s_waitcnt vmcnt(16)
	s_mov_b32 s100, 0
	s_branch .Lfw_3_b_pr0

.Lfw_3_b_pr0:
	s_barrier
	s_setprio 1
	v_mfma_f32_16x16x128_f8f6f4 v[106:109], v[198:205], v[18:25], 0
	v_mfma_f32_16x16x128_f8f6f4 v[98:101], v[206:213], v[18:25], 0
	v_mfma_f32_16x16x128_f8f6f4 v[90:93], v[198:205], v[26:33], 0
	v_mfma_f32_16x16x128_f8f6f4 v[82:85], v[206:213], v[26:33], 0
	v_mfma_f32_16x16x128_f8f6f4 v[74:77], v[198:205], v[34:41], 0
	v_mfma_f32_16x16x128_f8f6f4 v[66:69], v[206:213], v[34:41], 0
	v_mfma_f32_16x16x128_f8f6f4 v[58:61], v[198:205], v[42:49], 0
	v_mfma_f32_16x16x128_f8f6f4 v[50:53], v[206:213], v[42:49], 0
	s_setprio 0
	v_add_u32_e32 v14, 0x18000, v189
	s_barrier
	ds_read_b128 v[2:5], v14
	ds_read_b128 v[6:9], v14 offset:1024
	ds_read_b128 v[10:13], v14 offset:2048
	ds_read_b128 v[14:17], v14 offset:3072
	s_mov_b32 m0, s23
	ds_read_b128 v[18:21], v191 offset:32768
	ds_read_b128 v[22:25], v191 offset:33792
	ds_read_b128 v[26:29], v191 offset:34816
	ds_read_b128 v[30:33], v191 offset:35840
	ds_read_b128 v[34:37], v191 offset:36864
	ds_read_b128 v[38:41], v191 offset:37888
	ds_read_b128 v[42:45], v191 offset:38912
	ds_read_b128 v[46:49], v191 offset:39936
	buffer_load_dwordx4 v196, s[40:43], s57 offen lds
	s_mov_b32 m0, s24
	s_nop 0
	buffer_load_dwordx4 v197, s[40:43], s57 offen lds
	s_waitcnt lgkmcnt(8)
	s_barrier
	s_waitcnt lgkmcnt(0)
	s_setprio 1
	s_waitcnt lgkmcnt(6)
	v_mfma_f32_16x16x128_f8f6f4 v[174:177], v[2:9], v[18:25], v[174:177]
	v_mfma_f32_16x16x128_f8f6f4 v[166:169], v[10:17], v[18:25], v[166:169]
	s_waitcnt lgkmcnt(4)
	v_mfma_f32_16x16x128_f8f6f4 v[158:161], v[2:9], v[26:33], v[158:161]
	v_mfma_f32_16x16x128_f8f6f4 v[150:153], v[10:17], v[26:33], v[150:153]
	s_waitcnt lgkmcnt(2)
	v_mfma_f32_16x16x128_f8f6f4 v[142:145], v[2:9], v[34:41], v[142:145]
	v_mfma_f32_16x16x128_f8f6f4 v[134:137], v[10:17], v[34:41], v[134:137]
	s_waitcnt lgkmcnt(0)
	v_mfma_f32_16x16x128_f8f6f4 v[126:129], v[2:9], v[42:49], v[126:129]
	v_mfma_f32_16x16x128_f8f6f4 v[118:121], v[10:17], v[42:49], v[118:121]
	s_setprio 0
	s_barrier
	s_mov_b32 m0, s26
	v_add_u32_e32 v208, 0x1c000, v189
	ds_read_b128 v[196:199], v208
	ds_read_b128 v[200:203], v208 offset:1024
	ds_read_b128 v[204:207], v208 offset:2048
	ds_read_b128 v[208:211], v208 offset:3072
	buffer_load_dwordx4 v184, s[12:15], s7 offen lds
	s_add_i32 s7, s6, 0x10080
	s_mov_b32 m0, s27
	s_nop 0
	buffer_load_dwordx4 v184, s[12:15], s7 offen lds
	s_waitcnt vmcnt(10)
	s_barrier
	s_waitcnt lgkmcnt(0)
	s_setprio 1
	s_waitcnt lgkmcnt(2)
	v_mfma_f32_16x16x128_f8f6f4 v[170:173], v[196:203], v[18:25], v[170:173]
	s_waitcnt lgkmcnt(0)
	v_mfma_f32_16x16x128_f8f6f4 v[162:165], v[204:211], v[18:25], v[162:165]
	v_mfma_f32_16x16x128_f8f6f4 v[154:157], v[196:203], v[26:33], v[154:157]
	v_mfma_f32_16x16x128_f8f6f4 v[146:149], v[204:211], v[26:33], v[146:149]
	v_mfma_f32_16x16x128_f8f6f4 v[138:141], v[196:203], v[34:41], v[138:141]
	v_mfma_f32_16x16x128_f8f6f4 v[130:133], v[204:211], v[34:41], v[130:133]
	v_mfma_f32_16x16x128_f8f6f4 v[122:125], v[196:203], v[42:49], v[122:125]
	v_mfma_f32_16x16x128_f8f6f4 v[114:117], v[204:211], v[42:49], v[114:117]
	s_setprio 0
	s_mov_b32 m0, s28
	s_barrier
	ds_read_b128 v[18:21], v191 offset:49152
	ds_read_b128 v[22:25], v191 offset:50176
	ds_read_b128 v[26:29], v191 offset:51200
	ds_read_b128 v[30:33], v191 offset:52224
	ds_read_b128 v[34:37], v191 offset:53248
	ds_read_b128 v[38:41], v191 offset:54272
	ds_read_b128 v[42:45], v191 offset:55296
	ds_read_b128 v[46:49], v191 offset:56320
	buffer_load_dwordx4 v214, s[40:43], s51 offen lds
	s_mov_b32 m0, s29
	s_nop 0
	buffer_load_dwordx4 v215, s[40:43], s51 offen lds
	s_barrier
	s_waitcnt lgkmcnt(0)
	s_setprio 1
	s_waitcnt lgkmcnt(6)
	v_mfma_f32_16x16x128_f8f6f4 v[110:113], v[2:9], v[18:25], v[110:113]
	v_mfma_f32_16x16x128_f8f6f4 v[102:105], v[10:17], v[18:25], v[102:105]
	s_waitcnt lgkmcnt(4)
	v_mfma_f32_16x16x128_f8f6f4 v[94:97], v[2:9], v[26:33], v[94:97]
	v_mfma_f32_16x16x128_f8f6f4 v[86:89], v[10:17], v[26:33], v[86:89]
	s_waitcnt lgkmcnt(2)
	v_mfma_f32_16x16x128_f8f6f4 v[78:81], v[2:9], v[34:41], v[78:81]
	v_mfma_f32_16x16x128_f8f6f4 v[70:73], v[10:17], v[34:41], v[70:73]
	s_waitcnt lgkmcnt(0)
	v_mfma_f32_16x16x128_f8f6f4 v[62:65], v[2:9], v[42:49], v[62:65]
	v_mfma_f32_16x16x128_f8f6f4 v[54:57], v[10:17], v[42:49], v[54:57]
	s_setprio 0
	s_barrier
	s_mov_b32 m0, s30
	s_add_i32 s7, s6, 0x20080
	buffer_load_dwordx4 v184, s[12:15], s7 offen lds
	s_add_i32 s6, s6, 0x30080
	s_mov_b32 m0, s31
	s_nop 0
	buffer_load_dwordx4 v184, s[12:15], s6 offen lds
	s_waitcnt vmcnt(6)
	s_barrier
	s_setprio 1
	v_mfma_f32_16x16x128_f8f6f4 v[106:109], v[196:203], v[18:25], v[106:109]
	v_mfma_f32_16x16x128_f8f6f4 v[98:101], v[204:211], v[18:25], v[98:101]
	v_mfma_f32_16x16x128_f8f6f4 v[90:93], v[196:203], v[26:33], v[90:93]
	v_mfma_f32_16x16x128_f8f6f4 v[82:85], v[204:211], v[26:33], v[82:85]
	v_mfma_f32_16x16x128_f8f6f4 v[74:77], v[196:203], v[34:41], v[74:77]
	v_mfma_f32_16x16x128_f8f6f4 v[66:69], v[204:211], v[34:41], v[66:69]
	v_mfma_f32_16x16x128_f8f6f4 v[58:61], v[196:203], v[42:49], v[58:61]
	v_mfma_f32_16x16x128_f8f6f4 v[50:53], v[204:211], v[42:49], v[50:53]
	s_setprio 0
	s_add_i32 s8, s8, 2
	s_addk_i32 s9, 0x100
	s_cmp_gt_u32 s8, 5
	s_barrier
	s_cbranch_scc1 .LBB0_766
	s_branch .LBB0_775

.LBB0_1659:
	ds_read_b128 v[2:5], v190
	ds_read_b128 v[6:9], v190 offset:1024
	ds_read_b128 v[10:13], v190 offset:2048
	ds_read_b128 v[14:17], v190 offset:3072
	s_cmp_eq_u32 s8, 4
	s_cselect_b64 s[6:7], -1, 0
	s_add_i32 s14, s9, 0xffffff80
	s_cmp_lg_u32 s8, 4
	v_bfe_u32 v196, v186, 16, 16
	s_mov_b32 m0, s34
	v_lshl_add_u32 v196, v196, 10, v1
	v_bfe_u32 v197, v185, 16, 16
	ds_read_b128 v[42:45], v191
	ds_read_b128 v[46:49], v191 offset:1024
	ds_read_b128 v[34:37], v191 offset:2048
	ds_read_b128 v[38:41], v191 offset:3072
	ds_read_b128 v[26:29], v191 offset:4096
	ds_read_b128 v[30:33], v191 offset:5120
	ds_read_b128 v[18:21], v191 offset:6144
	ds_read_b128 v[22:25], v191 offset:7168
	buffer_load_dwordx4 v196, s[40:43], s14 offen lds
	v_lshl_add_u32 v197, v197, 10, v1
	s_mov_b32 m0, s35
	s_nop 0
	buffer_load_dwordx4 v197, s[40:43], s14 offen lds
	s_cbranch_scc1 .LBB0_1658
	v_mov_b32_e32 v197, v195
	v_mov_b32_e32 v196, v194
	v_mov_b32_e32 v185, v192
	v_mov_b32_e32 v186, v193
	s_branch .LBB0_1658
.LBB0_1659_pr1:
	ds_read_b128 v[2:5], v190
	ds_read_b128 v[6:9], v190 offset:1024
	ds_read_b128 v[10:13], v190 offset:2048
	ds_read_b128 v[14:17], v190 offset:3072
	s_cmp_eq_u32 s8, 4
	s_cselect_b64 s[6:7], -1, 0
	s_add_i32 s14, s9, 0xffffff80
	s_cmp_lg_u32 s8, 4
	v_bfe_u32 v196, v186, 16, 16
	s_mov_b32 m0, s34
	v_lshl_add_u32 v196, v196, 10, v1
	v_bfe_u32 v197, v185, 16, 16
	ds_read_b128 v[42:45], v191
	ds_read_b128 v[46:49], v191 offset:1024
	ds_read_b128 v[34:37], v191 offset:2048
	ds_read_b128 v[38:41], v191 offset:3072
	ds_read_b128 v[26:29], v191 offset:4096
	ds_read_b128 v[30:33], v191 offset:5120
	ds_read_b128 v[18:21], v191 offset:6144
	ds_read_b128 v[22:25], v191 offset:7168
	buffer_load_dwordx4 v196, s[40:43], s14 offen lds
	v_lshl_add_u32 v197, v197, 10, v1
	s_mov_b32 m0, s35
	s_nop 0
	buffer_load_dwordx4 v197, s[40:43], s14 offen lds
	s_cbranch_scc1 .LBB0_1658_pr1
	v_mov_b32_e32 v197, v195
	v_mov_b32_e32 v196, v194
	v_mov_b32_e32 v185, v192
	v_mov_b32_e32 v186, v193
	s_branch .LBB0_1658_pr1
.LBB0_1658_pr1:
	s_and_b64 s[14:15], s[6:7], exec
	s_cselect_b32 s59, 0, s9
	s_add_i32 s14, s57, s9
	s_or_b32 s58, s59, 0x80
	s_waitcnt lgkmcnt(8)
	s_barrier
	s_waitcnt lgkmcnt(0)
	s_and_b64 s[6:7], s[6:7], exec
	s_cselect_b32 s6, s46, s14
	s_add_i32 s7, s6, 0x80
	s_setprio 1
	s_waitcnt lgkmcnt(6)
	v_mfma_f32_16x16x128_f8f6f4 v[174:177], v[2:9], v[42:49], 0
	v_mfma_f32_16x16x128_f8f6f4 v[166:169], v[10:17], v[42:49], 0
	s_waitcnt lgkmcnt(4)
	v_mfma_f32_16x16x128_f8f6f4 v[158:161], v[2:9], v[34:41], 0
	v_mfma_f32_16x16x128_f8f6f4 v[150:153], v[10:17], v[34:41], 0
	s_waitcnt lgkmcnt(2)
	v_mfma_f32_16x16x128_f8f6f4 v[142:145], v[2:9], v[26:33], 0
	v_mfma_f32_16x16x128_f8f6f4 v[134:137], v[10:17], v[26:33], 0
	s_waitcnt lgkmcnt(0)
	v_mfma_f32_16x16x128_f8f6f4 v[126:129], v[2:9], v[18:25], 0
	v_mfma_f32_16x16x128_f8f6f4 v[118:121], v[10:17], v[18:25], 0
	s_setprio 0
	s_barrier
	s_mov_b32 m0, s18
	v_add_u32_e32 v210, 0x14000, v189
	s_mov_b32 s14, s42
	s_mov_b32 s15, s43
	ds_read_b128 v[198:201], v210
	ds_read_b128 v[202:205], v210 offset:1024
	ds_read_b128 v[206:209], v210 offset:2048
	ds_read_b128 v[210:213], v210 offset:3072
	buffer_load_dwordx4 v184, s[12:15], s6 offen lds
	s_add_i32 s33, s6, 0x10000
	s_mov_b32 m0, s19
	s_nop 0
	buffer_load_dwordx4 v184, s[12:15], s33 offen lds
	s_barrier
	s_waitcnt lgkmcnt(0)
	s_setprio 1
	s_waitcnt lgkmcnt(2)
	v_mfma_f32_16x16x128_f8f6f4 v[170:173], v[198:205], v[42:49], 0
	s_waitcnt lgkmcnt(0)
	v_mfma_f32_16x16x128_f8f6f4 v[162:165], v[206:213], v[42:49], 0
	v_mfma_f32_16x16x128_f8f6f4 v[154:157], v[198:205], v[34:41], 0
	v_mfma_f32_16x16x128_f8f6f4 v[146:149], v[206:213], v[34:41], 0
	v_mfma_f32_16x16x128_f8f6f4 v[138:141], v[198:205], v[26:33], 0
	v_mfma_f32_16x16x128_f8f6f4 v[130:133], v[206:213], v[26:33], 0
	v_mfma_f32_16x16x128_f8f6f4 v[122:125], v[198:205], v[18:25], 0
	v_mfma_f32_16x16x128_f8f6f4 v[114:117], v[206:213], v[18:25], 0
	s_setprio 0
	v_lshlrev_b32_e32 v214, 10, v186
	v_and_b32_e32 v214, 0x3fffc00, v214
	v_lshlrev_b32_e32 v215, 10, v185
	s_mov_b32 m0, s17
	v_add_u32_e32 v214, v214, v1
	v_and_b32_e32 v215, 0x3fffc00, v215
	s_barrier
	ds_read_b128 v[18:21], v191 offset:16384
	ds_read_b128 v[22:25], v191 offset:17408
	ds_read_b128 v[26:29], v191 offset:18432
	ds_read_b128 v[30:33], v191 offset:19456
	ds_read_b128 v[34:37], v191 offset:20480
	ds_read_b128 v[38:41], v191 offset:21504
	ds_read_b128 v[42:45], v191 offset:22528
	ds_read_b128 v[46:49], v191 offset:23552
	buffer_load_dwordx4 v214, s[40:43], s59 offen lds
	v_add_u32_e32 v215, v215, v1
	s_mov_b32 m0, s20
	s_nop 0
	buffer_load_dwordx4 v215, s[40:43], s59 offen lds
	s_barrier
	s_waitcnt lgkmcnt(0)
	s_setprio 1
	s_waitcnt lgkmcnt(6)
	v_mfma_f32_16x16x128_f8f6f4 v[110:113], v[2:9], v[18:25], 0
	v_mfma_f32_16x16x128_f8f6f4 v[102:105], v[10:17], v[18:25], 0
	s_waitcnt lgkmcnt(4)
	v_mfma_f32_16x16x128_f8f6f4 v[94:97], v[2:9], v[26:33], 0
	v_mfma_f32_16x16x128_f8f6f4 v[86:89], v[10:17], v[26:33], 0
	s_waitcnt lgkmcnt(2)
	v_mfma_f32_16x16x128_f8f6f4 v[78:81], v[2:9], v[34:41], 0
	v_mfma_f32_16x16x128_f8f6f4 v[70:73], v[10:17], v[34:41], 0
	s_waitcnt lgkmcnt(0)
	v_mfma_f32_16x16x128_f8f6f4 v[62:65], v[2:9], v[42:49], 0
	v_mfma_f32_16x16x128_f8f6f4 v[54:57], v[10:17], v[42:49], 0
	s_setprio 0
	s_barrier
	s_mov_b32 m0, s21
	s_add_i32 s33, s6, 0x20000
	buffer_load_dwordx4 v184, s[12:15], s33 offen lds
	s_add_i32 s33, s6, 0x30000
	s_mov_b32 m0, s22
	s_nop 0
	buffer_load_dwordx4 v184, s[12:15], s33 offen lds
	s_cmp_eq_u32 s100, 0
	s_cbranch_scc1 .Lfw_7_a_pr1
	s_waitcnt vmcnt(16)
	s_mov_b32 s100, 0
	s_branch .Lfw_7_b_pr1

.Lfw_7_b_pr1:
	s_barrier
	s_setprio 1
	v_mfma_f32_16x16x128_f8f6f4 v[106:109], v[198:205], v[18:25], 0
	v_mfma_f32_16x16x128_f8f6f4 v[98:101], v[206:213], v[18:25], 0
	v_mfma_f32_16x16x128_f8f6f4 v[90:93], v[198:205], v[26:33], 0
	v_mfma_f32_16x16x128_f8f6f4 v[82:85], v[206:213], v[26:33], 0
	v_mfma_f32_16x16x128_f8f6f4 v[74:77], v[198:205], v[34:41], 0
	v_mfma_f32_16x16x128_f8f6f4 v[66:69], v[206:213], v[34:41], 0
	v_mfma_f32_16x16x128_f8f6f4 v[58:61], v[198:205], v[42:49], 0
	v_mfma_f32_16x16x128_f8f6f4 v[50:53], v[206:213], v[42:49], 0
	s_setprio 0
	v_add_u32_e32 v14, 0x18000, v189
	s_barrier
	ds_read_b128 v[2:5], v14
	ds_read_b128 v[6:9], v14 offset:1024
	ds_read_b128 v[10:13], v14 offset:2048
	ds_read_b128 v[14:17], v14 offset:3072
	s_mov_b32 m0, s23
	ds_read_b128 v[18:21], v191 offset:32768
	ds_read_b128 v[22:25], v191 offset:33792
	ds_read_b128 v[26:29], v191 offset:34816
	ds_read_b128 v[30:33], v191 offset:35840
	ds_read_b128 v[34:37], v191 offset:36864
	ds_read_b128 v[38:41], v191 offset:37888
	ds_read_b128 v[42:45], v191 offset:38912
	ds_read_b128 v[46:49], v191 offset:39936
	buffer_load_dwordx4 v196, s[40:43], s59 offen lds
	s_mov_b32 m0, s24
	s_nop 0
	buffer_load_dwordx4 v197, s[40:43], s59 offen lds
	s_waitcnt lgkmcnt(8)
	s_barrier
	s_waitcnt lgkmcnt(0)
	s_setprio 1
	s_waitcnt lgkmcnt(6)
	v_mfma_f32_16x16x128_f8f6f4 v[174:177], v[2:9], v[18:25], v[174:177]
	v_mfma_f32_16x16x128_f8f6f4 v[166:169], v[10:17], v[18:25], v[166:169]
	s_waitcnt lgkmcnt(4)
	v_mfma_f32_16x16x128_f8f6f4 v[158:161], v[2:9], v[26:33], v[158:161]
	v_mfma_f32_16x16x128_f8f6f4 v[150:153], v[10:17], v[26:33], v[150:153]
	s_waitcnt lgkmcnt(2)
	v_mfma_f32_16x16x128_f8f6f4 v[142:145], v[2:9], v[34:41], v[142:145]
	v_mfma_f32_16x16x128_f8f6f4 v[134:137], v[10:17], v[34:41], v[134:137]
	s_waitcnt lgkmcnt(0)
	v_mfma_f32_16x16x128_f8f6f4 v[126:129], v[2:9], v[42:49], v[126:129]
	v_mfma_f32_16x16x128_f8f6f4 v[118:121], v[10:17], v[42:49], v[118:121]
	s_setprio 0
	s_barrier
	s_mov_b32 m0, s26
	v_add_u32_e32 v208, 0x1c000, v189
	ds_read_b128 v[196:199], v208
	ds_read_b128 v[200:203], v208 offset:1024
	ds_read_b128 v[204:207], v208 offset:2048
	ds_read_b128 v[208:211], v208 offset:3072
	buffer_load_dwordx4 v184, s[12:15], s7 offen lds
	s_add_i32 s7, s6, 0x10080
	s_mov_b32 m0, s27
	s_nop 0
	buffer_load_dwordx4 v184, s[12:15], s7 offen lds
	s_waitcnt vmcnt(10)
	s_barrier
	s_waitcnt lgkmcnt(0)
	s_setprio 1
	s_waitcnt lgkmcnt(2)
	v_mfma_f32_16x16x128_f8f6f4 v[170:173], v[196:203], v[18:25], v[170:173]
	s_waitcnt lgkmcnt(0)
	v_mfma_f32_16x16x128_f8f6f4 v[162:165], v[204:211], v[18:25], v[162:165]
	v_mfma_f32_16x16x128_f8f6f4 v[154:157], v[196:203], v[26:33], v[154:157]
	v_mfma_f32_16x16x128_f8f6f4 v[146:149], v[204:211], v[26:33], v[146:149]
	v_mfma_f32_16x16x128_f8f6f4 v[138:141], v[196:203], v[34:41], v[138:141]
	v_mfma_f32_16x16x128_f8f6f4 v[130:133], v[204:211], v[34:41], v[130:133]
	v_mfma_f32_16x16x128_f8f6f4 v[122:125], v[196:203], v[42:49], v[122:125]
	v_mfma_f32_16x16x128_f8f6f4 v[114:117], v[204:211], v[42:49], v[114:117]
	s_setprio 0
	s_mov_b32 m0, s28
	s_barrier
	ds_read_b128 v[18:21], v191 offset:49152
	ds_read_b128 v[22:25], v191 offset:50176
	ds_read_b128 v[26:29], v191 offset:51200
	ds_read_b128 v[30:33], v191 offset:52224
	ds_read_b128 v[34:37], v191 offset:53248
	ds_read_b128 v[38:41], v191 offset:54272
	ds_read_b128 v[42:45], v191 offset:55296
	ds_read_b128 v[46:49], v191 offset:56320
	buffer_load_dwordx4 v214, s[40:43], s58 offen lds
	s_mov_b32 m0, s29
	s_nop 0
	buffer_load_dwordx4 v215, s[40:43], s58 offen lds
	s_barrier
	s_waitcnt lgkmcnt(0)
	s_setprio 1
	s_waitcnt lgkmcnt(6)
	v_mfma_f32_16x16x128_f8f6f4 v[110:113], v[2:9], v[18:25], v[110:113]
	v_mfma_f32_16x16x128_f8f6f4 v[102:105], v[10:17], v[18:25], v[102:105]
	s_waitcnt lgkmcnt(4)
	v_mfma_f32_16x16x128_f8f6f4 v[94:97], v[2:9], v[26:33], v[94:97]
	v_mfma_f32_16x16x128_f8f6f4 v[86:89], v[10:17], v[26:33], v[86:89]
	s_waitcnt lgkmcnt(2)
	v_mfma_f32_16x16x128_f8f6f4 v[78:81], v[2:9], v[34:41], v[78:81]
	v_mfma_f32_16x16x128_f8f6f4 v[70:73], v[10:17], v[34:41], v[70:73]
	s_waitcnt lgkmcnt(0)
	v_mfma_f32_16x16x128_f8f6f4 v[62:65], v[2:9], v[42:49], v[62:65]
	v_mfma_f32_16x16x128_f8f6f4 v[54:57], v[10:17], v[42:49], v[54:57]
	s_setprio 0
	s_barrier
	s_mov_b32 m0, s30
	s_add_i32 s7, s6, 0x20080
	buffer_load_dwordx4 v184, s[12:15], s7 offen lds
	s_add_i32 s6, s6, 0x30080
	s_mov_b32 m0, s31
	s_nop 0
	buffer_load_dwordx4 v184, s[12:15], s6 offen lds
	s_waitcnt vmcnt(6)
	s_barrier
	s_setprio 1
	v_mfma_f32_16x16x128_f8f6f4 v[106:109], v[196:203], v[18:25], v[106:109]
	v_mfma_f32_16x16x128_f8f6f4 v[98:101], v[204:211], v[18:25], v[98:101]
	v_mfma_f32_16x16x128_f8f6f4 v[90:93], v[196:203], v[26:33], v[90:93]
	v_mfma_f32_16x16x128_f8f6f4 v[82:85], v[204:211], v[26:33], v[82:85]
	v_mfma_f32_16x16x128_f8f6f4 v[74:77], v[196:203], v[34:41], v[74:77]
	v_mfma_f32_16x16x128_f8f6f4 v[66:69], v[204:211], v[34:41], v[66:69]
	v_mfma_f32_16x16x128_f8f6f4 v[58:61], v[196:203], v[42:49], v[58:61]
	v_mfma_f32_16x16x128_f8f6f4 v[50:53], v[204:211], v[42:49], v[50:53]
	s_setprio 0
	s_add_i32 s8, s8, 2
	s_addk_i32 s9, 0x100
	s_cmp_gt_u32 s8, 5
	s_barrier
	s_cbranch_scc1 .LBB0_1650
	s_branch .LBB0_1659

.LBB0_2436:
	ds_read_b128 v[2:5], v190
	ds_read_b128 v[6:9], v190 offset:1024
	ds_read_b128 v[10:13], v190 offset:2048
	ds_read_b128 v[14:17], v190 offset:3072
	s_cmp_eq_u32 s8, 4
	s_cselect_b64 s[6:7], -1, 0
	s_add_i32 s14, s9, 0xffffff80
	s_cmp_lg_u32 s8, 4
	v_bfe_u32 v196, v186, 16, 16
	s_mov_b32 m0, s31
	v_lshl_add_u32 v196, v196, 10, v1
	v_bfe_u32 v197, v185, 16, 16
	ds_read_b128 v[42:45], v191
	ds_read_b128 v[46:49], v191 offset:1024
	ds_read_b128 v[34:37], v191 offset:2048
	ds_read_b128 v[38:41], v191 offset:3072
	ds_read_b128 v[26:29], v191 offset:4096
	ds_read_b128 v[30:33], v191 offset:5120
	ds_read_b128 v[18:21], v191 offset:6144
	ds_read_b128 v[22:25], v191 offset:7168
	buffer_load_dwordx4 v196, s[40:43], s14 offen lds
	v_lshl_add_u32 v197, v197, 10, v1
	s_mov_b32 m0, s34
	s_nop 0
	buffer_load_dwordx4 v197, s[40:43], s14 offen lds
	s_cbranch_scc1 .LBB0_2435
	v_mov_b32_e32 v197, v195
	v_mov_b32_e32 v196, v194
	v_mov_b32_e32 v185, v192
	v_mov_b32_e32 v186, v193
	s_branch .LBB0_2435
.LBB0_2436_pr2:
	ds_read_b128 v[2:5], v190
	ds_read_b128 v[6:9], v190 offset:1024
	ds_read_b128 v[10:13], v190 offset:2048
	ds_read_b128 v[14:17], v190 offset:3072
	s_cmp_eq_u32 s8, 4
	s_cselect_b64 s[6:7], -1, 0
	s_add_i32 s14, s9, 0xffffff80
	s_cmp_lg_u32 s8, 4
	v_bfe_u32 v196, v186, 16, 16
	s_mov_b32 m0, s31
	v_lshl_add_u32 v196, v196, 10, v1
	v_bfe_u32 v197, v185, 16, 16
	ds_read_b128 v[42:45], v191
	ds_read_b128 v[46:49], v191 offset:1024
	ds_read_b128 v[34:37], v191 offset:2048
	ds_read_b128 v[38:41], v191 offset:3072
	ds_read_b128 v[26:29], v191 offset:4096
	ds_read_b128 v[30:33], v191 offset:5120
	ds_read_b128 v[18:21], v191 offset:6144
	ds_read_b128 v[22:25], v191 offset:7168
	buffer_load_dwordx4 v196, s[40:43], s14 offen lds
	v_lshl_add_u32 v197, v197, 10, v1
	s_mov_b32 m0, s34
	s_nop 0
	buffer_load_dwordx4 v197, s[40:43], s14 offen lds
	s_cbranch_scc1 .LBB0_2435_pr2
	v_mov_b32_e32 v197, v195
	v_mov_b32_e32 v196, v194
	v_mov_b32_e32 v185, v192
	v_mov_b32_e32 v186, v193
	s_branch .LBB0_2435_pr2
.LBB0_2435_pr2:
	s_and_b64 s[14:15], s[6:7], exec
	s_cselect_b32 s58, 0, s9
	s_add_i32 s14, s49, s9
	s_or_b32 s57, s58, 0x80
	s_waitcnt lgkmcnt(8)
	s_barrier
	s_waitcnt lgkmcnt(0)
	s_and_b64 s[6:7], s[6:7], exec
	s_cselect_b32 s6, s45, s14
	s_add_i32 s7, s6, 0x80
	s_setprio 1
	s_waitcnt lgkmcnt(6)
	v_mfma_f32_16x16x128_f8f6f4 v[174:177], v[2:9], v[42:49], 0
	v_mfma_f32_16x16x128_f8f6f4 v[166:169], v[10:17], v[42:49], 0
	s_waitcnt lgkmcnt(4)
	v_mfma_f32_16x16x128_f8f6f4 v[158:161], v[2:9], v[34:41], 0
	v_mfma_f32_16x16x128_f8f6f4 v[150:153], v[10:17], v[34:41], 0
	s_waitcnt lgkmcnt(2)
	v_mfma_f32_16x16x128_f8f6f4 v[142:145], v[2:9], v[26:33], 0
	v_mfma_f32_16x16x128_f8f6f4 v[134:137], v[10:17], v[26:33], 0
	s_waitcnt lgkmcnt(0)
	v_mfma_f32_16x16x128_f8f6f4 v[126:129], v[2:9], v[18:25], 0
	v_mfma_f32_16x16x128_f8f6f4 v[118:121], v[10:17], v[18:25], 0
	s_setprio 0
	s_barrier
	s_mov_b32 m0, s17
	v_add_u32_e32 v210, 0x14000, v189
	s_mov_b32 s14, s42
	s_mov_b32 s15, s43
	ds_read_b128 v[198:201], v210
	ds_read_b128 v[202:205], v210 offset:1024
	ds_read_b128 v[206:209], v210 offset:2048
	ds_read_b128 v[210:213], v210 offset:3072
	buffer_load_dwordx4 v184, s[12:15], s6 offen lds
	s_add_i32 s33, s6, 0x10000
	s_mov_b32 m0, s18
	s_nop 0
	buffer_load_dwordx4 v184, s[12:15], s33 offen lds
	s_barrier
	s_waitcnt lgkmcnt(0)
	s_setprio 1
	s_waitcnt lgkmcnt(2)
	v_mfma_f32_16x16x128_f8f6f4 v[170:173], v[198:205], v[42:49], 0
	s_waitcnt lgkmcnt(0)
	v_mfma_f32_16x16x128_f8f6f4 v[162:165], v[206:213], v[42:49], 0
	v_mfma_f32_16x16x128_f8f6f4 v[154:157], v[198:205], v[34:41], 0
	v_mfma_f32_16x16x128_f8f6f4 v[146:149], v[206:213], v[34:41], 0
	v_mfma_f32_16x16x128_f8f6f4 v[138:141], v[198:205], v[26:33], 0
	v_mfma_f32_16x16x128_f8f6f4 v[130:133], v[206:213], v[26:33], 0
	v_mfma_f32_16x16x128_f8f6f4 v[122:125], v[198:205], v[18:25], 0
	v_mfma_f32_16x16x128_f8f6f4 v[114:117], v[206:213], v[18:25], 0
	s_setprio 0
	v_lshlrev_b32_e32 v214, 10, v186
	v_and_b32_e32 v214, 0x3fffc00, v214
	v_lshlrev_b32_e32 v215, 10, v185
	s_mov_b32 m0, s16
	v_add_u32_e32 v214, v214, v1
	v_and_b32_e32 v215, 0x3fffc00, v215
	s_barrier
	ds_read_b128 v[18:21], v191 offset:16384
	ds_read_b128 v[22:25], v191 offset:17408
	ds_read_b128 v[26:29], v191 offset:18432
	ds_read_b128 v[30:33], v191 offset:19456
	ds_read_b128 v[34:37], v191 offset:20480
	ds_read_b128 v[38:41], v191 offset:21504
	ds_read_b128 v[42:45], v191 offset:22528
	ds_read_b128 v[46:49], v191 offset:23552
	buffer_load_dwordx4 v214, s[40:43], s58 offen lds
	v_add_u32_e32 v215, v215, v1
	s_mov_b32 m0, s19
	s_nop 0
	buffer_load_dwordx4 v215, s[40:43], s58 offen lds
	s_barrier
	s_waitcnt lgkmcnt(0)
	s_setprio 1
	s_waitcnt lgkmcnt(6)
	v_mfma_f32_16x16x128_f8f6f4 v[110:113], v[2:9], v[18:25], 0
	v_mfma_f32_16x16x128_f8f6f4 v[102:105], v[10:17], v[18:25], 0
	s_waitcnt lgkmcnt(4)
	v_mfma_f32_16x16x128_f8f6f4 v[94:97], v[2:9], v[26:33], 0
	v_mfma_f32_16x16x128_f8f6f4 v[86:89], v[10:17], v[26:33], 0
	s_waitcnt lgkmcnt(2)
	v_mfma_f32_16x16x128_f8f6f4 v[78:81], v[2:9], v[34:41], 0
	v_mfma_f32_16x16x128_f8f6f4 v[70:73], v[10:17], v[34:41], 0
	s_waitcnt lgkmcnt(0)
	v_mfma_f32_16x16x128_f8f6f4 v[62:65], v[2:9], v[42:49], 0
	v_mfma_f32_16x16x128_f8f6f4 v[54:57], v[10:17], v[42:49], 0
	s_setprio 0
	s_barrier
	s_mov_b32 m0, s20
	s_add_i32 s33, s6, 0x20000
	buffer_load_dwordx4 v184, s[12:15], s33 offen lds
	s_add_i32 s33, s6, 0x30000
	s_mov_b32 m0, s21
	s_nop 0
	buffer_load_dwordx4 v184, s[12:15], s33 offen lds
	s_cmp_eq_u32 s100, 0
	s_cbranch_scc1 .Lfw_11_a_pr2
	s_waitcnt vmcnt(16)
	s_mov_b32 s100, 0
	s_branch .Lfw_11_b_pr2

.Lfw_11_b_pr2:
	s_barrier
	s_setprio 1
	v_mfma_f32_16x16x128_f8f6f4 v[106:109], v[198:205], v[18:25], 0
	v_mfma_f32_16x16x128_f8f6f4 v[98:101], v[206:213], v[18:25], 0
	v_mfma_f32_16x16x128_f8f6f4 v[90:93], v[198:205], v[26:33], 0
	v_mfma_f32_16x16x128_f8f6f4 v[82:85], v[206:213], v[26:33], 0
	v_mfma_f32_16x16x128_f8f6f4 v[74:77], v[198:205], v[34:41], 0
	v_mfma_f32_16x16x128_f8f6f4 v[66:69], v[206:213], v[34:41], 0
	v_mfma_f32_16x16x128_f8f6f4 v[58:61], v[198:205], v[42:49], 0
	v_mfma_f32_16x16x128_f8f6f4 v[50:53], v[206:213], v[42:49], 0
	s_setprio 0
	v_add_u32_e32 v14, 0x18000, v189
	s_barrier
	ds_read_b128 v[2:5], v14
	ds_read_b128 v[6:9], v14 offset:1024
	ds_read_b128 v[10:13], v14 offset:2048
	ds_read_b128 v[14:17], v14 offset:3072
	s_mov_b32 m0, s22
	ds_read_b128 v[18:21], v191 offset:32768
	ds_read_b128 v[22:25], v191 offset:33792
	ds_read_b128 v[26:29], v191 offset:34816
	ds_read_b128 v[30:33], v191 offset:35840
	ds_read_b128 v[34:37], v191 offset:36864
	ds_read_b128 v[38:41], v191 offset:37888
	ds_read_b128 v[42:45], v191 offset:38912
	ds_read_b128 v[46:49], v191 offset:39936
	buffer_load_dwordx4 v196, s[40:43], s58 offen lds
	s_mov_b32 m0, s23
	s_nop 0
	buffer_load_dwordx4 v197, s[40:43], s58 offen lds
	s_waitcnt lgkmcnt(8)
	s_barrier
	s_waitcnt lgkmcnt(0)
	s_setprio 1
	s_waitcnt lgkmcnt(6)
	v_mfma_f32_16x16x128_f8f6f4 v[174:177], v[2:9], v[18:25], v[174:177]
	v_mfma_f32_16x16x128_f8f6f4 v[166:169], v[10:17], v[18:25], v[166:169]
	s_waitcnt lgkmcnt(4)
	v_mfma_f32_16x16x128_f8f6f4 v[158:161], v[2:9], v[26:33], v[158:161]
	v_mfma_f32_16x16x128_f8f6f4 v[150:153], v[10:17], v[26:33], v[150:153]
	s_waitcnt lgkmcnt(2)
	v_mfma_f32_16x16x128_f8f6f4 v[142:145], v[2:9], v[34:41], v[142:145]
	v_mfma_f32_16x16x128_f8f6f4 v[134:137], v[10:17], v[34:41], v[134:137]
	s_waitcnt lgkmcnt(0)
	v_mfma_f32_16x16x128_f8f6f4 v[126:129], v[2:9], v[42:49], v[126:129]
	v_mfma_f32_16x16x128_f8f6f4 v[118:121], v[10:17], v[42:49], v[118:121]
	s_setprio 0
	s_barrier
	s_mov_b32 m0, s25
	v_add_u32_e32 v208, 0x1c000, v189
	ds_read_b128 v[196:199], v208
	ds_read_b128 v[200:203], v208 offset:1024
	ds_read_b128 v[204:207], v208 offset:2048
	ds_read_b128 v[208:211], v208 offset:3072
	buffer_load_dwordx4 v184, s[12:15], s7 offen lds
	s_add_i32 s7, s6, 0x10080
	s_mov_b32 m0, s26
	s_nop 0
	buffer_load_dwordx4 v184, s[12:15], s7 offen lds
	s_waitcnt vmcnt(10)
	s_barrier
	s_waitcnt lgkmcnt(0)
	s_setprio 1
	s_waitcnt lgkmcnt(2)
	v_mfma_f32_16x16x128_f8f6f4 v[170:173], v[196:203], v[18:25], v[170:173]
	s_waitcnt lgkmcnt(0)
	v_mfma_f32_16x16x128_f8f6f4 v[162:165], v[204:211], v[18:25], v[162:165]
	v_mfma_f32_16x16x128_f8f6f4 v[154:157], v[196:203], v[26:33], v[154:157]
	v_mfma_f32_16x16x128_f8f6f4 v[146:149], v[204:211], v[26:33], v[146:149]
	v_mfma_f32_16x16x128_f8f6f4 v[138:141], v[196:203], v[34:41], v[138:141]
	v_mfma_f32_16x16x128_f8f6f4 v[130:133], v[204:211], v[34:41], v[130:133]
	v_mfma_f32_16x16x128_f8f6f4 v[122:125], v[196:203], v[42:49], v[122:125]
	v_mfma_f32_16x16x128_f8f6f4 v[114:117], v[204:211], v[42:49], v[114:117]
	s_setprio 0
	s_mov_b32 m0, s27
	s_barrier
	ds_read_b128 v[18:21], v191 offset:49152
	ds_read_b128 v[22:25], v191 offset:50176
	ds_read_b128 v[26:29], v191 offset:51200
	ds_read_b128 v[30:33], v191 offset:52224
	ds_read_b128 v[34:37], v191 offset:53248
	ds_read_b128 v[38:41], v191 offset:54272
	ds_read_b128 v[42:45], v191 offset:55296
	ds_read_b128 v[46:49], v191 offset:56320
	buffer_load_dwordx4 v214, s[40:43], s57 offen lds
	s_mov_b32 m0, s28
	s_nop 0
	buffer_load_dwordx4 v215, s[40:43], s57 offen lds
	s_barrier
	s_waitcnt lgkmcnt(0)
	s_setprio 1
	s_waitcnt lgkmcnt(6)
	v_mfma_f32_16x16x128_f8f6f4 v[110:113], v[2:9], v[18:25], v[110:113]
	v_mfma_f32_16x16x128_f8f6f4 v[102:105], v[10:17], v[18:25], v[102:105]
	s_waitcnt lgkmcnt(4)
	v_mfma_f32_16x16x128_f8f6f4 v[94:97], v[2:9], v[26:33], v[94:97]
	v_mfma_f32_16x16x128_f8f6f4 v[86:89], v[10:17], v[26:33], v[86:89]
	s_waitcnt lgkmcnt(2)
	v_mfma_f32_16x16x128_f8f6f4 v[78:81], v[2:9], v[34:41], v[78:81]
	v_mfma_f32_16x16x128_f8f6f4 v[70:73], v[10:17], v[34:41], v[70:73]
	s_waitcnt lgkmcnt(0)
	v_mfma_f32_16x16x128_f8f6f4 v[62:65], v[2:9], v[42:49], v[62:65]
	v_mfma_f32_16x16x128_f8f6f4 v[54:57], v[10:17], v[42:49], v[54:57]
	s_setprio 0
	s_barrier
	s_mov_b32 m0, s29
	s_add_i32 s7, s6, 0x20080
	buffer_load_dwordx4 v184, s[12:15], s7 offen lds
	s_add_i32 s6, s6, 0x30080
	s_mov_b32 m0, s30
	s_nop 0
	buffer_load_dwordx4 v184, s[12:15], s6 offen lds
	s_waitcnt vmcnt(6)
	s_barrier
	s_setprio 1
	v_mfma_f32_16x16x128_f8f6f4 v[106:109], v[196:203], v[18:25], v[106:109]
	v_mfma_f32_16x16x128_f8f6f4 v[98:101], v[204:211], v[18:25], v[98:101]
	v_mfma_f32_16x16x128_f8f6f4 v[90:93], v[196:203], v[26:33], v[90:93]
	v_mfma_f32_16x16x128_f8f6f4 v[82:85], v[204:211], v[26:33], v[82:85]
	v_mfma_f32_16x16x128_f8f6f4 v[74:77], v[196:203], v[34:41], v[74:77]
	v_mfma_f32_16x16x128_f8f6f4 v[66:69], v[204:211], v[34:41], v[66:69]
	v_mfma_f32_16x16x128_f8f6f4 v[58:61], v[196:203], v[42:49], v[58:61]
	v_mfma_f32_16x16x128_f8f6f4 v[50:53], v[204:211], v[42:49], v[50:53]
	s_setprio 0
	s_add_i32 s8, s8, 2
	s_addk_i32 s9, 0x100
	s_cmp_gt_u32 s8, 5
	s_barrier
	s_cbranch_scc1 .LBB0_2423
	s_branch .LBB0_2436

.LBB0_3110:
	v_bfe_u32 v2, v194, 16, 16
	v_lshl_add_u32 v195, v2, 10, v184
	v_bfe_u32 v2, v193, 16, 16
	v_mov_b32_e32 v50, 0
	v_lshl_add_u32 v196, v2, 10, v184
	s_mov_b32 s8, -2
	s_movk_i32 s9, 0x100
	s_branch .LBB0_3112_pr3

.LBB0_3112:
	ds_read_b128 v[2:5], v191
	ds_read_b128 v[6:9], v191 offset:1024
	ds_read_b128 v[10:13], v191 offset:2048
	ds_read_b128 v[14:17], v191 offset:3072
	s_cmp_eq_u32 s8, 4
	s_cselect_b64 s[6:7], -1, 0
	s_add_i32 s14, s9, 0xffffff80
	s_cmp_lg_u32 s8, 4
	v_bfe_u32 v197, v187, 16, 16
	s_mov_b32 m0, s31
	v_lshl_add_u32 v197, v197, 10, v184
	v_bfe_u32 v198, v186, 16, 16
	ds_read_b128 v[42:45], v192
	ds_read_b128 v[46:49], v192 offset:1024
	ds_read_b128 v[34:37], v192 offset:2048
	ds_read_b128 v[38:41], v192 offset:3072
	ds_read_b128 v[26:29], v192 offset:4096
	ds_read_b128 v[30:33], v192 offset:5120
	ds_read_b128 v[18:21], v192 offset:6144
	ds_read_b128 v[22:25], v192 offset:7168
	buffer_load_dwordx4 v197, s[40:43], s14 offen lds
	v_lshl_add_u32 v198, v198, 10, v184
	s_mov_b32 m0, s34
	s_nop 0
	buffer_load_dwordx4 v198, s[40:43], s14 offen lds
	s_cbranch_scc1 .LBB0_3111
	v_mov_b32_e32 v198, v196
	v_mov_b32_e32 v197, v195
	v_mov_b32_e32 v186, v193
	v_mov_b32_e32 v187, v194
	s_branch .LBB0_3111
.LBB0_3112_pr3:
	ds_read_b128 v[2:5], v191
	ds_read_b128 v[6:9], v191 offset:1024
	ds_read_b128 v[10:13], v191 offset:2048
	ds_read_b128 v[14:17], v191 offset:3072
	s_cmp_eq_u32 s8, 4
	s_cselect_b64 s[6:7], -1, 0
	s_add_i32 s14, s9, 0xffffff80
	s_cmp_lg_u32 s8, 4
	v_bfe_u32 v197, v187, 16, 16
	s_mov_b32 m0, s31
	v_lshl_add_u32 v197, v197, 10, v184
	v_bfe_u32 v198, v186, 16, 16
	ds_read_b128 v[42:45], v192
	ds_read_b128 v[46:49], v192 offset:1024
	ds_read_b128 v[34:37], v192 offset:2048
	ds_read_b128 v[38:41], v192 offset:3072
	ds_read_b128 v[26:29], v192 offset:4096
	ds_read_b128 v[30:33], v192 offset:5120
	ds_read_b128 v[18:21], v192 offset:6144
	ds_read_b128 v[22:25], v192 offset:7168
	buffer_load_dwordx4 v197, s[40:43], s14 offen lds
	v_lshl_add_u32 v198, v198, 10, v184
	s_mov_b32 m0, s34
	s_nop 0
	buffer_load_dwordx4 v198, s[40:43], s14 offen lds
	s_cbranch_scc1 .LBB0_3111_pr3
	v_mov_b32_e32 v198, v196
	v_mov_b32_e32 v197, v195
	v_mov_b32_e32 v186, v193
	v_mov_b32_e32 v187, v194
	s_branch .LBB0_3111_pr3
.LBB0_3111_pr3:
	s_and_b64 s[14:15], s[6:7], exec
	s_cselect_b32 s57, 0, s9
	s_add_i32 s14, s50, s9
	s_or_b32 s51, s57, 0x80
	s_waitcnt lgkmcnt(8)
	s_barrier
	s_waitcnt lgkmcnt(0)
	s_and_b64 s[6:7], s[6:7], exec
	s_cselect_b32 s6, s45, s14
	s_add_i32 s7, s6, 0x80
	s_setprio 1
	s_waitcnt lgkmcnt(6)
	v_mfma_f32_16x16x128_f8f6f4 v[174:177], v[2:9], v[42:49], 0
	v_mfma_f32_16x16x128_f8f6f4 v[166:169], v[10:17], v[42:49], 0
	s_waitcnt lgkmcnt(4)
	v_mfma_f32_16x16x128_f8f6f4 v[158:161], v[2:9], v[34:41], 0
	v_mfma_f32_16x16x128_f8f6f4 v[150:153], v[10:17], v[34:41], 0
	s_waitcnt lgkmcnt(2)
	v_mfma_f32_16x16x128_f8f6f4 v[142:145], v[2:9], v[26:33], 0
	v_mfma_f32_16x16x128_f8f6f4 v[134:137], v[10:17], v[26:33], 0
	s_waitcnt lgkmcnt(0)
	v_mfma_f32_16x16x128_f8f6f4 v[126:129], v[2:9], v[18:25], 0
	v_mfma_f32_16x16x128_f8f6f4 v[118:121], v[10:17], v[18:25], 0
	s_setprio 0
	s_barrier
	s_mov_b32 m0, s17
	v_add_u32_e32 v199, 0x14000, v190
	s_mov_b32 s14, s42
	s_mov_b32 s15, s43
	ds_read_b128 v[200:203], v199
	ds_read_b128 v[204:207], v199 offset:1024
	ds_read_b128 v[208:211], v199 offset:2048
	ds_read_b128 v[212:215], v199 offset:3072
	buffer_load_dwordx4 v185, s[12:15], s6 offen lds
	s_add_i32 s33, s6, 0x10000
	s_mov_b32 m0, s18
	s_nop 0
	buffer_load_dwordx4 v185, s[12:15], s33 offen lds
	s_barrier
	s_waitcnt lgkmcnt(0)
	s_setprio 1
	s_waitcnt lgkmcnt(2)
	v_mfma_f32_16x16x128_f8f6f4 v[170:173], v[200:207], v[42:49], 0
	s_waitcnt lgkmcnt(0)
	v_mfma_f32_16x16x128_f8f6f4 v[162:165], v[208:215], v[42:49], 0
	v_mfma_f32_16x16x128_f8f6f4 v[154:157], v[200:207], v[34:41], 0
	v_mfma_f32_16x16x128_f8f6f4 v[146:149], v[208:215], v[34:41], 0
	v_mfma_f32_16x16x128_f8f6f4 v[138:141], v[200:207], v[26:33], 0
	v_mfma_f32_16x16x128_f8f6f4 v[130:133], v[208:215], v[26:33], 0
	v_mfma_f32_16x16x128_f8f6f4 v[122:125], v[200:207], v[18:25], 0
	v_mfma_f32_16x16x128_f8f6f4 v[114:117], v[208:215], v[18:25], 0
	s_setprio 0
	v_lshlrev_b32_e32 v199, 10, v187
	v_and_b32_e32 v199, 0x3fffc00, v199
	v_add_u32_e32 v216, v199, v184
	v_lshlrev_b32_e32 v199, 10, v186
	s_mov_b32 m0, s16
	v_and_b32_e32 v199, 0x3fffc00, v199
	s_barrier
	ds_read_b128 v[18:21], v192 offset:16384
	ds_read_b128 v[22:25], v192 offset:17408
	ds_read_b128 v[26:29], v192 offset:18432
	ds_read_b128 v[30:33], v192 offset:19456
	ds_read_b128 v[34:37], v192 offset:20480
	ds_read_b128 v[38:41], v192 offset:21504
	ds_read_b128 v[42:45], v192 offset:22528
	ds_read_b128 v[46:49], v192 offset:23552
	buffer_load_dwordx4 v216, s[40:43], s57 offen lds
	v_add_u32_e32 v217, v199, v184
	s_mov_b32 m0, s19
	s_nop 0
	buffer_load_dwordx4 v217, s[40:43], s57 offen lds
	s_barrier
	s_waitcnt lgkmcnt(0)
	s_setprio 1
	s_waitcnt lgkmcnt(6)
	v_mfma_f32_16x16x128_f8f6f4 v[110:113], v[2:9], v[18:25], 0
	v_mfma_f32_16x16x128_f8f6f4 v[102:105], v[10:17], v[18:25], 0
	s_waitcnt lgkmcnt(4)
	v_mfma_f32_16x16x128_f8f6f4 v[94:97], v[2:9], v[26:33], 0
	v_mfma_f32_16x16x128_f8f6f4 v[86:89], v[10:17], v[26:33], 0
	s_waitcnt lgkmcnt(2)
	v_mfma_f32_16x16x128_f8f6f4 v[78:81], v[2:9], v[34:41], 0
	v_mfma_f32_16x16x128_f8f6f4 v[70:73], v[10:17], v[34:41], 0
	s_waitcnt lgkmcnt(0)
	v_mfma_f32_16x16x128_f8f6f4 v[62:65], v[2:9], v[42:49], 0
	v_mfma_f32_16x16x128_f8f6f4 v[54:57], v[10:17], v[42:49], 0
	s_setprio 0
	s_barrier
	s_mov_b32 m0, s20
	s_add_i32 s33, s6, 0x20000
	buffer_load_dwordx4 v185, s[12:15], s33 offen lds
	s_add_i32 s33, s6, 0x30000
	s_mov_b32 m0, s21
	s_nop 0
	buffer_load_dwordx4 v185, s[12:15], s33 offen lds
	s_cmp_eq_u32 s100, 0
	s_cbranch_scc1 .Lfw_15_a_pr3
	s_waitcnt vmcnt(16)
	s_mov_b32 s100, 0
	s_branch .Lfw_15_b_pr3

.Lfw_15_b_pr3:
	s_barrier
	s_setprio 1
	v_mfma_f32_16x16x128_f8f6f4 v[106:109], v[200:207], v[18:25], 0
	v_mfma_f32_16x16x128_f8f6f4 v[98:101], v[208:215], v[18:25], 0
	v_mfma_f32_16x16x128_f8f6f4 v[90:93], v[200:207], v[26:33], 0
	v_mfma_f32_16x16x128_f8f6f4 v[82:85], v[208:215], v[26:33], 0
	v_mfma_f32_16x16x128_f8f6f4 v[74:77], v[200:207], v[34:41], 0
	v_mfma_f32_16x16x128_f8f6f4 v[66:69], v[208:215], v[34:41], 0
	v_mfma_f32_16x16x128_f8f6f4 v[58:61], v[200:207], v[42:49], 0
	v_mfma_f32_16x16x128_f8f6f4 v[50:53], v[208:215], v[42:49], 0
	s_setprio 0
	v_add_u32_e32 v14, 0x18000, v190
	s_barrier
	ds_read_b128 v[2:5], v14
	ds_read_b128 v[6:9], v14 offset:1024
	ds_read_b128 v[10:13], v14 offset:2048
	ds_read_b128 v[14:17], v14 offset:3072
	s_mov_b32 m0, s22
	ds_read_b128 v[18:21], v192 offset:32768
	ds_read_b128 v[22:25], v192 offset:33792
	ds_read_b128 v[26:29], v192 offset:34816
	ds_read_b128 v[30:33], v192 offset:35840
	ds_read_b128 v[34:37], v192 offset:36864
	ds_read_b128 v[38:41], v192 offset:37888
	ds_read_b128 v[42:45], v192 offset:38912
	ds_read_b128 v[46:49], v192 offset:39936
	buffer_load_dwordx4 v197, s[40:43], s57 offen lds
	s_mov_b32 m0, s23
	s_nop 0
	buffer_load_dwordx4 v198, s[40:43], s57 offen lds
	s_waitcnt lgkmcnt(8)
	s_barrier
	s_waitcnt lgkmcnt(0)
	s_setprio 1
	s_waitcnt lgkmcnt(6)
	v_mfma_f32_16x16x128_f8f6f4 v[174:177], v[2:9], v[18:25], v[174:177]
	v_mfma_f32_16x16x128_f8f6f4 v[166:169], v[10:17], v[18:25], v[166:169]
	s_waitcnt lgkmcnt(4)
	v_mfma_f32_16x16x128_f8f6f4 v[158:161], v[2:9], v[26:33], v[158:161]
	v_mfma_f32_16x16x128_f8f6f4 v[150:153], v[10:17], v[26:33], v[150:153]
	s_waitcnt lgkmcnt(2)
	v_mfma_f32_16x16x128_f8f6f4 v[142:145], v[2:9], v[34:41], v[142:145]
	v_mfma_f32_16x16x128_f8f6f4 v[134:137], v[10:17], v[34:41], v[134:137]
	s_waitcnt lgkmcnt(0)
	v_mfma_f32_16x16x128_f8f6f4 v[126:129], v[2:9], v[42:49], v[126:129]
	v_mfma_f32_16x16x128_f8f6f4 v[118:121], v[10:17], v[42:49], v[118:121]
	s_setprio 0
	s_barrier
	s_mov_b32 m0, s25
	v_add_u32_e32 v197, 0x1c000, v190
	ds_read_b128 v[198:201], v197
	ds_read_b128 v[202:205], v197 offset:1024
	ds_read_b128 v[206:209], v197 offset:2048
	ds_read_b128 v[210:213], v197 offset:3072
	buffer_load_dwordx4 v185, s[12:15], s7 offen lds
	s_add_i32 s7, s6, 0x10080
	s_mov_b32 m0, s26
	s_nop 0
	buffer_load_dwordx4 v185, s[12:15], s7 offen lds
	s_waitcnt vmcnt(10)
	s_barrier
	s_waitcnt lgkmcnt(0)
	s_setprio 1
	s_waitcnt lgkmcnt(2)
	v_mfma_f32_16x16x128_f8f6f4 v[170:173], v[198:205], v[18:25], v[170:173]
	s_waitcnt lgkmcnt(0)
	v_mfma_f32_16x16x128_f8f6f4 v[162:165], v[206:213], v[18:25], v[162:165]
	v_mfma_f32_16x16x128_f8f6f4 v[154:157], v[198:205], v[26:33], v[154:157]
	v_mfma_f32_16x16x128_f8f6f4 v[146:149], v[206:213], v[26:33], v[146:149]
	v_mfma_f32_16x16x128_f8f6f4 v[138:141], v[198:205], v[34:41], v[138:141]
	v_mfma_f32_16x16x128_f8f6f4 v[130:133], v[206:213], v[34:41], v[130:133]
	v_mfma_f32_16x16x128_f8f6f4 v[122:125], v[198:205], v[42:49], v[122:125]
	v_mfma_f32_16x16x128_f8f6f4 v[114:117], v[206:213], v[42:49], v[114:117]
	s_setprio 0
	s_mov_b32 m0, s27
	s_barrier
	ds_read_b128 v[18:21], v192 offset:49152
	ds_read_b128 v[22:25], v192 offset:50176
	ds_read_b128 v[26:29], v192 offset:51200
	ds_read_b128 v[30:33], v192 offset:52224
	ds_read_b128 v[34:37], v192 offset:53248
	ds_read_b128 v[38:41], v192 offset:54272
	ds_read_b128 v[42:45], v192 offset:55296
	ds_read_b128 v[46:49], v192 offset:56320
	buffer_load_dwordx4 v216, s[40:43], s51 offen lds
	s_mov_b32 m0, s28
	s_nop 0
	buffer_load_dwordx4 v217, s[40:43], s51 offen lds
	s_barrier
	s_waitcnt lgkmcnt(0)
	s_setprio 1
	s_waitcnt lgkmcnt(6)
	v_mfma_f32_16x16x128_f8f6f4 v[110:113], v[2:9], v[18:25], v[110:113]
	v_mfma_f32_16x16x128_f8f6f4 v[102:105], v[10:17], v[18:25], v[102:105]
	s_waitcnt lgkmcnt(4)
	v_mfma_f32_16x16x128_f8f6f4 v[94:97], v[2:9], v[26:33], v[94:97]
	v_mfma_f32_16x16x128_f8f6f4 v[86:89], v[10:17], v[26:33], v[86:89]
	s_waitcnt lgkmcnt(2)
	v_mfma_f32_16x16x128_f8f6f4 v[78:81], v[2:9], v[34:41], v[78:81]
	v_mfma_f32_16x16x128_f8f6f4 v[70:73], v[10:17], v[34:41], v[70:73]
	s_waitcnt lgkmcnt(0)
	v_mfma_f32_16x16x128_f8f6f4 v[62:65], v[2:9], v[42:49], v[62:65]
	v_mfma_f32_16x16x128_f8f6f4 v[54:57], v[10:17], v[42:49], v[54:57]
	s_setprio 0
	s_barrier
	s_mov_b32 m0, s29
	s_add_i32 s7, s6, 0x20080
	buffer_load_dwordx4 v185, s[12:15], s7 offen lds
	s_add_i32 s6, s6, 0x30080
	s_mov_b32 m0, s30
	s_nop 0
	buffer_load_dwordx4 v185, s[12:15], s6 offen lds
	s_waitcnt vmcnt(6)
	s_barrier
	s_setprio 1
	v_mfma_f32_16x16x128_f8f6f4 v[106:109], v[198:205], v[18:25], v[106:109]
	v_mfma_f32_16x16x128_f8f6f4 v[98:101], v[206:213], v[18:25], v[98:101]
	v_mfma_f32_16x16x128_f8f6f4 v[90:93], v[198:205], v[26:33], v[90:93]
	v_mfma_f32_16x16x128_f8f6f4 v[82:85], v[206:213], v[26:33], v[82:85]
	v_mfma_f32_16x16x128_f8f6f4 v[74:77], v[198:205], v[34:41], v[74:77]
	v_mfma_f32_16x16x128_f8f6f4 v[66:69], v[206:213], v[34:41], v[66:69]
	v_mfma_f32_16x16x128_f8f6f4 v[58:61], v[198:205], v[42:49], v[58:61]
	v_mfma_f32_16x16x128_f8f6f4 v[50:53], v[206:213], v[42:49], v[50:53]
	s_setprio 0
	s_add_i32 s8, s8, 2
	s_addk_i32 s9, 0x100
	s_cmp_gt_u32 s8, 5
	s_barrier
	s_cbranch_scc1 .LBB0_3099
	s_branch .LBB0_3112
